# MoBA unit-loop top barrier: dropped the store-drain vmcnt(0) that syncthreads added (lgkmcnt(0) kept); previous unit's output stores now drain under the work-queue atomic and first loads
# baseline (speedup 1.0000x reference)
.LBB0_871:
	s_add_i32 s10, s55, s2
	s_and_b32 s16, s10, 7
	s_waitcnt lgkmcnt(0)
	s_barrier
	s_and_saveexec_b64 s[10:11], s[38:39]
	s_cbranch_execz .LBB0_875
	s_mov_b64 s[14:15], exec
	v_mbcnt_lo_u32_b32 v2, s14, 0
	v_mbcnt_hi_u32_b32 v2, s15, v2
	v_cmp_eq_u32_e32 vcc, 0, v2
	s_and_saveexec_b64 s[12:13], vcc
	s_cbranch_execz .LBB0_874
	s_lshl_b32 s17, s16, 8
	s_bcnt1_i32_b64 s14, s[14:15]
	v_mov_b32_e32 v4, s17
	v_mov_b32_e32 v5, s14
	global_atomic_add v4, v4, v5, s[94:95] offset:256 sc0
